# ffn-up entry: the eight w_out panel counters polled with one load instead of eight serial polls
# speedup vs baseline: 1.0011x; 1.0011x over previous
; __device__ __forceinline__ void acq_agent() { __builtin_amdgcn_fence(__ATOMIC_ACQUIRE, "agent"); asm volatile("s_waitcnt vmcnt(0)" ::: "memory"); }
; __device__ __forceinline__ void poll_ge(const unsigned* cnt, unsigned need) {
;     unsigned sp = 0;
;     while ((unsigned)__builtin_amdgcn_readfirstlane((int)__hip_atomic_load((unsigned*)cnt, __ATOMIC_RELAXED, __HIP_MEMORY_SCOPE_AGENT)) < need) { __builtin_amdgcn_s_sleep(2); if (++sp > (1u << 22)) break; }
; }
; #pragma unroll 1
;         for (int i = 0; i < 8; ++i) pg8::poll_ge(c + 64 * i, n);
;         pg8::acq_agent(); } __syncthreads(); }
.LBB0_1994:
	v_readlane_b32 s16, v254, 1
	v_readlane_b32 s17, v254, 2
	s_load_dwordx4 s[48:51], s[16:17], 0x118
	v_readlane_b32 s0, v254, 0
	v_readlane_b32 s24, v255, 44
	s_waitcnt lgkmcnt(0)
	s_mov_b32 s13, s57
	s_mov_b32 s29, s0
	s_cmpk_eq_i32 s24, 0x100
	s_cselect_b64 s[0:1], -1, 0
	s_cmpk_lg_i32 s24, 0x100
	s_cselect_b64 s[2:3], -1, 0
	s_and_b64 vcc, exec, s[0:1]
	s_cbranch_vccz .LBB0_2008
	v_readlane_b32 s4, v254, 40
	v_readlane_b32 s5, v254, 41
	s_and_b64 vcc, exec, s[4:5]
	s_cbranch_vccnz .LBB0_2007
	s_lshl_b32 s4, s29, 3
	s_and_b32 s4, s4, 56
	v_readlane_b32 s6, v254, 47
	s_or_b32 s4, s4, s6
	s_lshl_b32 s56, s4, 6
	s_lshl_b64 s[4:5], s[56:57], 2
	s_add_u32 s4, s50, s4
	s_addc_u32 s5, s51, s5
	s_add_u32 s8, s4, 0xd0c00
	s_addc_u32 s9, s5, 0
	s_mov_b32 s10, 0
	v_readlane_b32 s7, v254, 48
	v_mbcnt_lo_u32_b32 v0, -1, 0
	v_mbcnt_hi_u32_b32 v0, -1, v0
	v_and_b32_e32 v0, 7, v0
	v_lshlrev_b32_e32 v0, 8, v0
	s_mov_b32 s11, 0x100000
.Lw8_poll:
	global_load_dword v2, v0, s[8:9] sc1
	s_waitcnt vmcnt(0)
	v_cmp_gt_u32_e32 vcc, 32, v2
	s_cmp_eq_u64 vcc, 0
	s_cbranch_scc1 .LBB0_2006
	s_sleep 2
	s_add_i32 s11, s11, -1
	s_cmp_lg_u32 s11, 0
	s_cbranch_scc1 .Lw8_poll
